# attention phase: workgroups with blockIdx bit 3 start about 2us later (desynchronised per-item store/load bursts)
# baseline (speedup 1.0000x reference)
.LBB0_877:
	s_or_b64 exec, exec, s[0:1]
	v_lshrrev_b32_e32 v244, 1, v254
	v_and_b32_e32 v244, 0x80, v244
	v_xor_b32_e32 v244, v244, v254
	v_mov_b32_e32 v1, v244
	s_waitcnt lgkmcnt(0)
	s_barrier
	s_bitcmp0_b32 s2, 3
	s_cbranch_scc1 .Lstg9_go
	s_sleep 64
.Lstg9_go:
	s_cmp_lg_u32 0, -1
	v_lshrrev_b32_e32 v5, 2, v1
	v_lshrrev_b32_e32 v2, 5, v1
	v_lshlrev_b32_e32 v4, 2, v1
	v_and_b32_e32 v6, 2, v5
	v_and_or_b32 v4, v4, 12, v6
	v_xor_b32_e32 v6, v2, v5
	v_and_or_b32 v4, v6, 1, v4
	v_lshrrev_b32_e32 v6, 1, v1
	v_and_b32_e32 v0, 31, v1
	v_xor_b32_e32 v2, v2, v6
	v_lshlrev_b32_e32 v7, 7, v0
	v_lshlrev_b32_e32 v2, 4, v2
	v_lshlrev_b32_e32 v6, 3, v1
	v_bfe_u32 v3, v1, 5, 1
	v_and_or_b32 v2, v2, 16, v7
	v_and_b32_e32 v7, 0x60, v6
	v_bfe_u32 v8, v1, 2, 2
	v_and_b32_e32 v6, 8, v6
	s_cselect_b32 s0, 0, 0
	v_lshrrev_b32_e32 v9, 3, v1
	v_lshlrev_b32_e32 v12, 10, v3
	v_lshlrev_b32_e32 v13, 8, v8
	v_add_u32_e32 v6, s0, v6
	v_and_b32_e32 v10, 2, v9
	v_bfe_u32 v11, v1, 1, 1
	v_add3_u32 v6, v6, v12, v13
	v_or_b32_e32 v13, 2, v3
	v_lshlrev_b32_e32 v0, 8, v0
	v_bitop3_b32 v12, v10, v3, v11 bitop3:0x36
	v_bitop3_b32 v10, v10, v13, v11 bitop3:0x36
	v_lshl_or_b32 v198, v4, 4, v0
	v_lshlrev_b32_e32 v0, 4, v1
	v_lshlrev_b32_e32 v10, 4, v10
	s_movk_i32 s0, 0x800
	v_lshlrev_b32_e32 v8, 6, v8
	s_movk_i32 s16, 0x4000
	v_and_b32_e32 v0, 0x1f0, v0
	v_lshl_add_u32 v12, v12, 4, v6
	v_add3_u32 v6, v6, v10, s0
	v_xor_b32_e32 v10, 64, v8
	v_or3_b32 v199, v2, v7, s16
	v_lshl_or_b32 v2, v3, 9, v0
	v_mov_b32_e32 v0, 0
	v_add_u32_e32 v188, v12, v8
	v_add_u32_e32 v189, v6, v8
	v_add_u32_e32 v192, v12, v10
	v_add_u32_e32 v193, v6, v10
	v_xor_b32_e32 v10, 0x80, v8
	v_xor_b32_e32 v8, 0xc0, v8
	v_mov_b32_e32 v3, v0
	v_add_u32_e32 v196, v12, v8
	v_add_u32_e32 v197, v6, v8
	v_lshl_add_u64 v[162:163], s[36:37], 0, v[2:3]
	v_and_b32_e32 v2, 15, v1
	v_and_b32_e32 v5, 12, v5
	v_bfe_u32 v8, v1, 6, 2
	v_bitop3_b32 v2, v5, v2, v8 bitop3:0x36
	s_not_b32 s0, s2
	v_add_u32_e32 v3, 0x200, v1
	v_lshrrev_b32_e32 v4, 4, v1
	v_lshlrev_b32_e32 v2, 4, v2
	s_movk_i32 s7, 0x180
	s_add_i32 s17, s30, s0
	v_mad_u64_u32 v[164:165], s[0:1], v4, s7, v[2:3]
	v_bfe_u32 v7, v1, 4, 5
	v_lshrrev_b32_e32 v5, 4, v3
	s_mov_b32 s0, 0x1ffffe0
	v_add_u32_e32 v195, v6, v10
	s_movk_i32 s6, 0xc0
	v_ashrrev_i32_e32 v6, 6, v1
	v_ashrrev_i32_e32 v200, 8, v1
	v_and_or_b32 v5, v5, s0, v7
	v_xor_b32_e32 v1, v4, v1
	v_mad_u64_u32 v[166:167], s[0:1], v5, s7, v[2:3]
	v_mul_lo_u32 v5, v9, s6
	v_lshlrev_b32_e32 v1, 3, v1
	v_and_or_b32 v1, v1, 56, v5
	v_mov_b32_e32 v5, 0x100
	v_lshlrev_b32_e32 v4, 10, v6
	v_lshl_add_u32 v168, v1, 1, v5
	v_lshrrev_b32_e32 v1, 9, v3
	v_mul_u32_u24_e32 v1, 0x3000, v1
	v_mul_u32_u24_e32 v3, 0x180, v7
	v_add_u32_e32 v203, 0, v4
	s_mov_b32 s3, 0
	v_add_u32_e32 v194, v12, v10
	v_and_b32_e32 v201, 3, v6
	v_mov_b32_e32 v165, v0
	v_mov_b32_e32 v167, v0
	v_mov_b32_e32 v169, v0
	s_movk_i32 s36, 0x3000
	v_add3_u32 v170, v1, v3, v2
	s_movk_i32 s37, 0x1000
	s_movk_i32 s40, 0x2000
	v_add_u32_e32 v204, 0x2000, v203
	v_add_u32_e32 v205, 0x4000, v203
	s_mov_b64 s[0:1], 0x1dc06000
	s_mov_b32 s41, 0x8000
	s_mov_b64 s[6:7], 0x1dc0c000
	s_movk_i32 s44, 0xfe0
	s_movk_i32 s45, 0x2200
	s_mov_b32 s50, 0xc000
	s_mov_b32 s51, 0x10000
	s_mov_b32 s52, 0x14000
	s_mov_b32 s53, 0x18000
	v_mbcnt_hi_u32_b32 v191, -1, v186
	v_readfirstlane_b32 s74, v203
	v_readfirstlane_b32 s76, v244
	s_nop 0
	s_bfe_u32 s76, s76, 0x10007
	v_xor_b32_e32 v171, 0x20, v198
	v_xor_b32_e32 v174, 0x40, v198
	v_xor_b32_e32 v175, 0x60, v198
	v_xor_b32_e32 v176, 0x80, v198
	v_xor_b32_e32 v177, 0xa0, v198
	v_xor_b32_e32 v178, 0xc0, v198
	v_xor_b32_e32 v179, 0xe0, v198
	v_xor_b32_e32 v202, 0x20, v199
	v_xor_b32_e32 v207, 0x40, v199
	v_xor_b32_e32 v208, 0x60, v199
	v_mov_b32_e32 v1, 0x23ff8
	v_mov_b32_e32 v180, 0
	ds_write_b32 v1, v180
	s_mov_b32 s78, 0
	s_mov_b32 s54, 0
	s_branch .LBB0_879
